# no per-segment setprio in GEMM K-loops + one static s_setprio 1 for waves 0-3 for the duration of each GEMM phase
# speedup vs baseline: 1.0116x; 1.0116x over previous
; #define KWS() ((unsigned char*)*(const float* const __attribute__((address_space(4)))*)(kfresh(kargp) + 128))
; __global__ void __launch_bounds__(512, 2) mega_fwd(Args args) {
;     ...
;             unsigned char* ws = KWS();
;             pg8::Gemm gm{(const bf16*)(ws + WS_XB), (const bf16*)(ws + WS_WIN), M_TOK, NPROJ, DM}; pg8::StaticOrder S; S.init(M_TOK, NPROJ, G, (int)blockIdx.x);
;             pg8::EpiBf16S<0> E{(bf16*)(ws + WS_PROJ), NPROJ, (const float*)(ws + WS_SSQ) + (L == 0 ? 0 : 2 * 16384)};
;     ...
;             int reps = 2; asm volatile("" : "+s"(reps));
;             for (int rep = 0; rep < reps; ++rep)
;     ...
;             pg8::gemm_phase<pg8::EpiBf16S<0>, pg8::StaticOrder, true, true>(lds, gm, S, E);
.LBB0_256:
	s_or_b64 exec, exec, s[16:17]
	v_readfirstlane_b32 s2, v202
	s_nop 3
	s_cmp_ge_u32 s2, 0x100
	s_cbranch_scc1 .Lhp_skip0
	s_setprio 1
